# attn-B L segment: 6 redundant VALU removed; dilated attention: skip O-rescale while running max is still the -1e30 sentinel in all lanes
# speedup vs baseline: 1.0044x; 1.0016x over previous
.Lam_done_0:
	v_max_f32_e32 v36, v20, v21
	v_max3_f32 v36, v36, v22, v23
	v_max3_f32 v36, v36, v24, v25
	v_max3_f32 v36, v36, v26, v27
	v_max3_f32 v36, v36, v28, v29
	v_max3_f32 v36, v36, v30, v31
	v_max3_f32 v36, v36, v32, v33
	v_max3_f32 v36, v36, v34, v35
	v_max3_f32 v36, v36, v4, v5
	v_max3_f32 v36, v36, v6, v7
	v_max3_f32 v36, v36, v8, v9
	v_max3_f32 v36, v36, v10, v11
	v_max3_f32 v36, v36, v12, v13
	v_max3_f32 v36, v36, v14, v15
	v_max3_f32 v36, v36, v16, v17
	v_max3_f32 v36, v36, v18, v19
	v_mov_b32_e32 v37, v36
	s_nop 1
	v_permlane32_swap_b32_e32 v36, v37
	s_mov_b32 s16, 0xf149f2ca
	v_max3_f32 v212, v36, v37, s16
	v_sub_f32_e32 v20, v20, v212
	v_exp_f32_e32 v37, v20
	v_sub_f32_e32 v20, v21, v212
	v_exp_f32_e32 v38, v20
	v_sub_f32_e32 v20, v22, v212
	v_exp_f32_e32 v39, v20
	v_sub_f32_e32 v20, v23, v212
	v_exp_f32_e32 v23, v20
	v_sub_f32_e32 v20, v24, v212
	v_exp_f32_e32 v24, v20
	v_sub_f32_e32 v20, v25, v212
	v_add_f32_e32 v21, 0, v37
	v_exp_f32_e32 v25, v20
	v_sub_f32_e32 v20, v26, v212
	v_add_f32_e32 v21, v38, v21
	v_exp_f32_e32 v26, v20
	v_sub_f32_e32 v20, v27, v212
	v_add_f32_e32 v21, v39, v21
	v_exp_f32_e32 v27, v20
	v_sub_f32_e32 v20, v28, v212
	v_add_f32_e32 v21, v23, v21
	v_exp_f32_e32 v28, v20
	v_sub_f32_e32 v20, v29, v212
	v_add_f32_e32 v21, v24, v21
	v_exp_f32_e32 v29, v20
	v_sub_f32_e32 v20, v30, v212
	v_add_f32_e32 v21, v25, v21
	v_exp_f32_e32 v30, v20
	v_sub_f32_e32 v20, v31, v212
	v_add_f32_e32 v21, v26, v21
	v_exp_f32_e32 v31, v20
	v_sub_f32_e32 v20, v32, v212
	v_add_f32_e32 v21, v27, v21
	v_exp_f32_e32 v32, v20
	v_sub_f32_e32 v20, v33, v212
	v_add_f32_e32 v21, v28, v21
	v_exp_f32_e32 v33, v20
	v_sub_f32_e32 v20, v34, v212
	v_add_f32_e32 v21, v29, v21
	v_exp_f32_e32 v34, v20
	v_sub_f32_e32 v20, v35, v212
	v_add_f32_e32 v21, v30, v21
	v_sub_f32_e32 v4, v4, v212
	v_exp_f32_e32 v35, v20
	v_add_f32_e32 v21, v31, v21
	v_sub_f32_e32 v5, v5, v212
	v_exp_f32_e32 v4, v4
	v_add_f32_e32 v21, v32, v21
	v_sub_f32_e32 v6, v6, v212
	v_exp_f32_e32 v5, v5
	v_add_f32_e32 v21, v33, v21
	v_sub_f32_e32 v7, v7, v212
	v_exp_f32_e32 v6, v6
	v_add_f32_e32 v21, v34, v21
	v_sub_f32_e32 v8, v8, v212
	v_exp_f32_e32 v7, v7
	v_add_f32_e32 v21, v35, v21
	v_sub_f32_e32 v9, v9, v212
	v_exp_f32_e32 v8, v8
	v_add_f32_e32 v21, v4, v21
	v_sub_f32_e32 v10, v10, v212
	v_exp_f32_e32 v9, v9
	v_add_f32_e32 v21, v5, v21
	v_sub_f32_e32 v11, v11, v212
	v_exp_f32_e32 v10, v10
	v_add_f32_e32 v21, v6, v21
	v_sub_f32_e32 v12, v12, v212
	v_exp_f32_e32 v11, v11
	v_add_f32_e32 v21, v7, v21
	v_sub_f32_e32 v13, v13, v212
	v_exp_f32_e32 v12, v12
	v_add_f32_e32 v21, v8, v21
	v_sub_f32_e32 v14, v14, v212
	v_exp_f32_e32 v13, v13
	v_add_f32_e32 v21, v9, v21
	v_sub_f32_e32 v15, v15, v212
	v_exp_f32_e32 v14, v14
	v_add_f32_e32 v21, v10, v21
	v_sub_f32_e32 v16, v16, v212
	v_exp_f32_e32 v15, v15
	v_add_f32_e32 v21, v11, v21
	v_sub_f32_e32 v17, v17, v212
	v_exp_f32_e32 v16, v16
	v_add_f32_e32 v21, v12, v21
	v_sub_f32_e32 v18, v18, v212
	v_exp_f32_e32 v17, v17
	v_add_f32_e32 v21, v13, v21
	v_sub_f32_e32 v19, v19, v212
	v_exp_f32_e32 v18, v18
	v_add_f32_e32 v21, v14, v21
	v_exp_f32_e32 v19, v19
	v_add_f32_e32 v21, v15, v21
	v_sub_f32_e32 v36, 0xf149f2ca, v212
	v_add_f32_e32 v21, v16, v21
	v_exp_f32_e32 v20, v36
	v_add_f32_e32 v21, v17, v21
	v_add_f32_e32 v21, v18, v21
	v_add_f32_e32 v21, v19, v21
	v_mov_b32_e32 v22, v21
	s_nop 1
	v_permlane32_swap_b32_e32 v21, v22
	v_cmp_gt_f32_e32 vcc, 1.0, v20
	v_cvt_pk_bf16_f32 v82, v37, v38
	v_cvt_pk_bf16_f32 v83, v39, v23
	v_cvt_pk_bf16_f32 v84, v24, v25
	v_cvt_pk_bf16_f32 v85, v26, v27
	v_cvt_pk_bf16_f32 v78, v28, v29
	v_cvt_pk_bf16_f32 v79, v30, v31
	v_cvt_pk_bf16_f32 v80, v32, v33
	v_cvt_pk_bf16_f32 v81, v34, v35
	v_cvt_pk_bf16_f32 v74, v4, v5
	v_cvt_pk_bf16_f32 v75, v6, v7
	v_cvt_pk_bf16_f32 v76, v8, v9
	v_cvt_pk_bf16_f32 v77, v10, v11
	v_cvt_pk_bf16_f32 v70, v12, v13
	v_cvt_pk_bf16_f32 v71, v14, v15
	v_cvt_pk_bf16_f32 v72, v16, v17
	v_cvt_pk_bf16_f32 v73, v18, v19
	s_branch .LBB0_559
	s_and_saveexec_b64 s[22:23], s[38:39]
	ds_write_b32 v191, v20 offset:128
	s_or_b64 exec, exec, s[22:23]
	s_waitcnt lgkmcnt(0)
	v_lshl_add_u32 v12, v185, 2, s44
	ds_read_b128 v[4:7], v12 offset:224
	ds_read_b128 v[8:11], v12 offset:192
	ds_read_b128 v[24:27], v12 offset:160
	ds_read_b128 v[28:31], v12 offset:128
	s_waitcnt lgkmcnt(3)
	v_pk_mul_f32 v[18:19], v[6:7], 0 op_sel_hi:[1,0]
	s_waitcnt lgkmcnt(2)
	v_pk_mul_f32 v[14:15], v[10:11], 0 op_sel_hi:[1,0]
	s_waitcnt lgkmcnt(1)
	v_pk_mul_f32 v[10:11], v[26:27], 0 op_sel_hi:[1,0]
	s_waitcnt lgkmcnt(0)
	v_pk_mul_f32 v[6:7], v[30:31], 0 op_sel_hi:[1,0]
	v_pk_mul_f32 v[16:17], v[4:5], 0 op_sel_hi:[1,0]
	v_pk_mul_f32 v[12:13], v[8:9], 0 op_sel_hi:[1,0]
	v_pk_mul_f32 v[8:9], v[24:25], 0 op_sel_hi:[1,0]
	v_pk_mul_f32 v[4:5], v[28:29], 0 op_sel_hi:[1,0]
	s_branch .LBB0_560

.Lam_done_1:
	v_max_f32_e32 v134, v86, v87
	v_max3_f32 v134, v134, v88, v89
	v_max3_f32 v134, v134, v90, v91
	v_max3_f32 v134, v134, v92, v93
	v_max3_f32 v134, v134, v94, v95
	v_max3_f32 v134, v134, v96, v97
	v_max3_f32 v134, v134, v98, v99
	v_max3_f32 v134, v134, v100, v101
	v_max3_f32 v134, v134, v70, v71
	v_max3_f32 v134, v134, v72, v73
	v_max3_f32 v134, v134, v74, v75
	v_max3_f32 v134, v134, v76, v77
	v_max3_f32 v134, v134, v78, v79
	v_max3_f32 v134, v134, v80, v81
	v_max3_f32 v134, v134, v82, v83
	v_max3_f32 v134, v134, v84, v85
	v_mov_b32_e32 v135, v134
	s_nop 1
	v_permlane32_swap_b32_e32 v134, v135
	v_max3_f32 v211, v212, v134, v135
	v_cmp_eq_u32_e32 vcc, 0xf149f2ca, v212
	s_nop 0
	s_cmp_eq_u64 vcc, exec
	s_cselect_b32 s100, 1, 0
	v_sub_f32_e32 v86, v86, v211
	v_exp_f32_e32 v135, v86
	v_sub_f32_e32 v86, v87, v211
	v_exp_f32_e32 v136, v86
	v_sub_f32_e32 v86, v88, v211
	v_exp_f32_e32 v137, v86
	v_sub_f32_e32 v86, v89, v211
	v_exp_f32_e32 v89, v86
	v_sub_f32_e32 v86, v90, v211
	v_exp_f32_e32 v90, v86
	v_sub_f32_e32 v86, v91, v211
	v_exp_f32_e32 v91, v86
	v_sub_f32_e32 v86, v92, v211
	v_exp_f32_e32 v92, v86
	v_sub_f32_e32 v86, v93, v211
	v_exp_f32_e32 v93, v86
	v_sub_f32_e32 v86, v94, v211
	v_exp_f32_e32 v94, v86
	v_sub_f32_e32 v86, v95, v211
	v_exp_f32_e32 v95, v86
	v_sub_f32_e32 v86, v96, v211
	v_exp_f32_e32 v96, v86
	v_sub_f32_e32 v86, v97, v211
	v_exp_f32_e32 v97, v86
	v_sub_f32_e32 v86, v98, v211
	v_exp_f32_e32 v98, v86
	v_sub_f32_e32 v86, v99, v211
	v_exp_f32_e32 v99, v86
	v_sub_f32_e32 v86, v100, v211
	v_sub_f32_e32 v134, v212, v211
	v_sub_f32_e32 v74, v74, v211
	v_exp_f32_e32 v100, v86
	v_sub_f32_e32 v86, v101, v211
	v_exp_f32_e32 v101, v86
	v_exp_f32_e32 v86, v134
	v_exp_f32_e32 v134, v74
	v_add_f32_e32 v74, 0, v135
	v_add_f32_e32 v74, v136, v74
	v_add_f32_e32 v74, v137, v74
	v_add_f32_e32 v74, v89, v74
	v_add_f32_e32 v74, v90, v74
	v_add_f32_e32 v74, v91, v74
	v_add_f32_e32 v74, v92, v74
	v_add_f32_e32 v74, v93, v74
	v_add_f32_e32 v74, v94, v74
	v_add_f32_e32 v74, v95, v74
	v_add_f32_e32 v74, v96, v74
	v_sub_f32_e32 v70, v70, v211
	v_add_f32_e32 v74, v97, v74
	v_sub_f32_e32 v71, v71, v211
	v_exp_f32_e32 v70, v70
	v_add_f32_e32 v74, v98, v74
	v_sub_f32_e32 v72, v72, v211
	v_exp_f32_e32 v71, v71
	v_add_f32_e32 v74, v99, v74
	v_sub_f32_e32 v73, v73, v211
	v_exp_f32_e32 v72, v72
	v_add_f32_e32 v74, v100, v74
	v_exp_f32_e32 v73, v73
	v_add_f32_e32 v74, v101, v74
	v_sub_f32_e32 v75, v75, v211
	v_add_f32_e32 v74, v70, v74
	v_sub_f32_e32 v76, v76, v211
	v_exp_f32_e32 v138, v75
	v_add_f32_e32 v74, v71, v74
	v_sub_f32_e32 v77, v77, v211
	v_exp_f32_e32 v139, v76
	v_add_f32_e32 v74, v72, v74
	v_sub_f32_e32 v78, v78, v211
	v_exp_f32_e32 v77, v77
	v_add_f32_e32 v74, v73, v74
	v_sub_f32_e32 v79, v79, v211
	v_exp_f32_e32 v140, v78
	v_add_f32_e32 v74, v134, v74
	v_sub_f32_e32 v80, v80, v211
	v_exp_f32_e32 v141, v79
	v_add_f32_e32 v74, v138, v74
	v_sub_f32_e32 v81, v81, v211
	v_exp_f32_e32 v174, v80
	v_add_f32_e32 v74, v139, v74
	v_sub_f32_e32 v82, v82, v211
	v_exp_f32_e32 v175, v81
	v_add_f32_e32 v74, v77, v74
	v_sub_f32_e32 v83, v83, v211
	v_exp_f32_e32 v176, v82
	v_add_f32_e32 v74, v140, v74
	v_sub_f32_e32 v84, v84, v211
	v_exp_f32_e32 v177, v83
	v_add_f32_e32 v74, v141, v74
	v_sub_f32_e32 v85, v85, v211
	v_exp_f32_e32 v178, v84
	v_add_f32_e32 v74, v174, v74
	v_exp_f32_e32 v179, v85
	v_add_f32_e32 v74, v175, v74
	v_add_f32_e32 v74, v176, v74
	v_add_f32_e32 v74, v177, v74
	v_add_f32_e32 v74, v178, v74
	v_add_f32_e32 v87, v179, v74
	v_mov_b32_e32 v88, v87
	s_nop 1
	v_permlane32_swap_b32_e32 v87, v88
	v_cmp_gt_f32_e32 vcc, 1.0, v86
	v_cvt_pk_bf16_f32 v82, v135, v136
	v_cvt_pk_bf16_f32 v83, v137, v89
	v_cvt_pk_bf16_f32 v84, v90, v91
	v_cvt_pk_bf16_f32 v85, v92, v93
	v_cvt_pk_bf16_f32 v78, v94, v95
	v_cvt_pk_bf16_f32 v79, v96, v97
	v_cvt_pk_bf16_f32 v80, v98, v99
	v_cvt_pk_bf16_f32 v81, v100, v101
	v_cvt_pk_bf16_f32 v74, v70, v71
	v_cvt_pk_bf16_f32 v75, v72, v73
	v_cvt_pk_bf16_f32 v76, v134, v138
	v_cvt_pk_bf16_f32 v77, v139, v77
	v_cvt_pk_bf16_f32 v70, v140, v141
	v_cvt_pk_bf16_f32 v71, v174, v175
	v_cvt_pk_bf16_f32 v72, v176, v177
	v_cvt_pk_bf16_f32 v73, v178, v179
	s_cmp_lg_u32 s100, 0
	s_cbranch_scc1 .LBB0_566
	s_cbranch_vccz .LBB0_566
	s_and_saveexec_b64 s[22:23], s[38:39]
	ds_write_b32 v191, v86 offset:128
	s_or_b64 exec, exec, s[22:23]
	s_waitcnt lgkmcnt(0)
	v_lshl_add_u32 v89, v185, 2, s44
	ds_read_b128 v[90:93], v89 offset:224
	ds_read_b128 v[94:97], v89 offset:192
	ds_read_b128 v[98:101], v89 offset:160
	ds_read_b128 v[134:137], v89 offset:128
	s_waitcnt lgkmcnt(3)
	v_pk_mul_f32 v[34:35], v[34:35], v[92:93]
	s_waitcnt lgkmcnt(2)
	v_pk_mul_f32 v[30:31], v[30:31], v[96:97]
	s_waitcnt lgkmcnt(1)
	v_pk_mul_f32 v[26:27], v[26:27], v[100:101]
	s_waitcnt lgkmcnt(0)
	v_pk_mul_f32 v[22:23], v[22:23], v[136:137]
	v_pk_mul_f32 v[32:33], v[32:33], v[90:91]
	v_pk_mul_f32 v[28:29], v[28:29], v[94:95]
	v_pk_mul_f32 v[24:25], v[24:25], v[98:99]
	v_pk_mul_f32 v[20:21], v[20:21], v[134:135]
	v_pk_mul_f32 v[50:51], v[50:51], v[92:93]
	v_pk_mul_f32 v[46:47], v[46:47], v[96:97]
	v_pk_mul_f32 v[42:43], v[42:43], v[100:101]
	v_pk_mul_f32 v[38:39], v[38:39], v[136:137]
	v_pk_mul_f32 v[48:49], v[48:49], v[90:91]
	v_pk_mul_f32 v[44:45], v[44:45], v[94:95]
	v_pk_mul_f32 v[40:41], v[40:41], v[98:99]
	v_pk_mul_f32 v[36:37], v[36:37], v[134:135]
	v_pk_mul_f32 v[66:67], v[66:67], v[92:93]
	v_pk_mul_f32 v[62:63], v[62:63], v[96:97]
	v_pk_mul_f32 v[58:59], v[58:59], v[100:101]
	v_pk_mul_f32 v[54:55], v[54:55], v[136:137]
	v_pk_mul_f32 v[64:65], v[64:65], v[90:91]
	v_pk_mul_f32 v[60:61], v[60:61], v[94:95]
	v_pk_mul_f32 v[56:57], v[56:57], v[98:99]
	v_pk_mul_f32 v[52:53], v[52:53], v[134:135]
	v_pk_mul_f32 v[18:19], v[18:19], v[92:93]
	v_pk_mul_f32 v[14:15], v[14:15], v[96:97]
	v_pk_mul_f32 v[10:11], v[10:11], v[100:101]
	v_pk_mul_f32 v[6:7], v[6:7], v[136:137]
	v_pk_mul_f32 v[16:17], v[16:17], v[90:91]
	v_pk_mul_f32 v[12:13], v[12:13], v[94:95]
	v_pk_mul_f32 v[8:9], v[8:9], v[98:99]
	v_pk_mul_f32 v[4:5], v[4:5], v[134:135]

.Lam_done_2:
	v_max_f32_e32 v166, v86, v87
	v_max3_f32 v166, v166, v88, v89
	v_max3_f32 v166, v166, v90, v91
	v_max3_f32 v166, v166, v92, v93
	v_max3_f32 v166, v166, v94, v95
	v_max3_f32 v166, v166, v96, v97
	v_max3_f32 v166, v166, v98, v99
	v_max3_f32 v166, v166, v100, v101
	v_max3_f32 v166, v166, v70, v71
	v_max3_f32 v166, v166, v72, v73
	v_max3_f32 v166, v166, v74, v75
	v_max3_f32 v166, v166, v76, v77
	v_max3_f32 v166, v166, v78, v79
	v_max3_f32 v166, v166, v80, v81
	v_max3_f32 v166, v166, v82, v83
	v_max3_f32 v166, v166, v84, v85
	v_mov_b32_e32 v167, v166
	s_nop 1
	v_permlane32_swap_b32_e32 v166, v167
	v_max3_f32 v212, v211, v166, v167
	v_cmp_eq_u32_e32 vcc, 0xf149f2ca, v211
	s_nop 0
	s_cmp_eq_u64 vcc, exec
	s_cselect_b32 s100, 1, 0
	v_sub_f32_e32 v86, v86, v212
	v_exp_f32_e32 v167, v86
	v_sub_f32_e32 v86, v87, v212
	v_exp_f32_e32 v168, v86
	v_sub_f32_e32 v86, v88, v212
	v_exp_f32_e32 v169, v86
	v_sub_f32_e32 v86, v89, v212
	v_exp_f32_e32 v89, v86
	v_sub_f32_e32 v86, v90, v212
	v_exp_f32_e32 v90, v86
	v_sub_f32_e32 v86, v91, v212
	v_exp_f32_e32 v91, v86
	v_sub_f32_e32 v86, v92, v212
	v_exp_f32_e32 v92, v86
	v_sub_f32_e32 v86, v93, v212
	v_exp_f32_e32 v93, v86
	v_sub_f32_e32 v86, v94, v212
	v_exp_f32_e32 v94, v86
	v_sub_f32_e32 v86, v95, v212
	v_exp_f32_e32 v95, v86
	v_sub_f32_e32 v86, v96, v212
	v_exp_f32_e32 v96, v86
	v_sub_f32_e32 v86, v97, v212
	v_exp_f32_e32 v97, v86
	v_sub_f32_e32 v86, v98, v212
	v_exp_f32_e32 v98, v86
	v_sub_f32_e32 v86, v99, v212
	v_exp_f32_e32 v99, v86
	v_sub_f32_e32 v86, v100, v212
	v_sub_f32_e32 v166, v211, v212
	v_sub_f32_e32 v74, v74, v212
	v_exp_f32_e32 v100, v86
	v_sub_f32_e32 v86, v101, v212
	v_exp_f32_e32 v101, v86
	v_exp_f32_e32 v86, v166
	v_exp_f32_e32 v166, v74
	v_add_f32_e32 v74, 0, v167
	v_add_f32_e32 v74, v168, v74
	v_add_f32_e32 v74, v169, v74
	v_add_f32_e32 v74, v89, v74
	v_add_f32_e32 v74, v90, v74
	v_add_f32_e32 v74, v91, v74
	v_add_f32_e32 v74, v92, v74
	v_add_f32_e32 v74, v93, v74
	v_add_f32_e32 v74, v94, v74
	v_add_f32_e32 v74, v95, v74
	v_add_f32_e32 v74, v96, v74
	v_sub_f32_e32 v70, v70, v212
	v_add_f32_e32 v74, v97, v74
	v_sub_f32_e32 v71, v71, v212
	v_exp_f32_e32 v70, v70
	v_add_f32_e32 v74, v98, v74
	v_sub_f32_e32 v72, v72, v212
	v_exp_f32_e32 v71, v71
	v_add_f32_e32 v74, v99, v74
	v_sub_f32_e32 v73, v73, v212
	v_exp_f32_e32 v72, v72
	v_add_f32_e32 v74, v100, v74
	v_exp_f32_e32 v73, v73
	v_add_f32_e32 v74, v101, v74
	v_sub_f32_e32 v75, v75, v212
	v_add_f32_e32 v74, v70, v74
	v_sub_f32_e32 v76, v76, v212
	v_exp_f32_e32 v170, v75
	v_add_f32_e32 v74, v71, v74
	v_sub_f32_e32 v77, v77, v212
	v_exp_f32_e32 v171, v76
	v_add_f32_e32 v74, v72, v74
	v_sub_f32_e32 v78, v78, v212
	v_exp_f32_e32 v77, v77
	v_add_f32_e32 v74, v73, v74
	v_sub_f32_e32 v79, v79, v212
	v_exp_f32_e32 v172, v78
	v_add_f32_e32 v74, v166, v74
	v_sub_f32_e32 v80, v80, v212
	v_exp_f32_e32 v173, v79
	v_add_f32_e32 v74, v170, v74
	v_sub_f32_e32 v81, v81, v212
	v_exp_f32_e32 v174, v80
	v_add_f32_e32 v74, v171, v74
	v_sub_f32_e32 v82, v82, v212
	v_exp_f32_e32 v175, v81
	v_add_f32_e32 v74, v77, v74
	v_sub_f32_e32 v83, v83, v212
	v_exp_f32_e32 v176, v82
	v_add_f32_e32 v74, v172, v74
	v_sub_f32_e32 v84, v84, v212
	v_exp_f32_e32 v177, v83
	v_add_f32_e32 v74, v173, v74
	v_sub_f32_e32 v85, v85, v212
	v_exp_f32_e32 v178, v84
	v_add_f32_e32 v74, v174, v74
	v_exp_f32_e32 v179, v85
	v_add_f32_e32 v74, v175, v74
	v_add_f32_e32 v74, v176, v74
	v_add_f32_e32 v74, v177, v74
	v_add_f32_e32 v74, v178, v74
	v_add_f32_e32 v87, v179, v74
	v_mov_b32_e32 v88, v87
	s_nop 1
	v_permlane32_swap_b32_e32 v87, v88
	v_cmp_gt_f32_e32 vcc, 1.0, v86
	v_cvt_pk_bf16_f32 v82, v167, v168
	v_cvt_pk_bf16_f32 v83, v169, v89
	v_cvt_pk_bf16_f32 v84, v90, v91
	v_cvt_pk_bf16_f32 v85, v92, v93
	v_cvt_pk_bf16_f32 v78, v94, v95
	v_cvt_pk_bf16_f32 v79, v96, v97
	v_cvt_pk_bf16_f32 v80, v98, v99
	v_cvt_pk_bf16_f32 v81, v100, v101
	v_cvt_pk_bf16_f32 v74, v70, v71
	v_cvt_pk_bf16_f32 v75, v72, v73
	v_cvt_pk_bf16_f32 v76, v166, v170
	v_cvt_pk_bf16_f32 v77, v171, v77
	v_cvt_pk_bf16_f32 v70, v172, v173
	v_cvt_pk_bf16_f32 v71, v174, v175
	v_cvt_pk_bf16_f32 v72, v176, v177
	v_cvt_pk_bf16_f32 v73, v178, v179
	s_cmp_lg_u32 s100, 0
	s_cbranch_scc1 .LBB0_573
	s_cbranch_vccz .LBB0_573
	s_and_saveexec_b64 s[22:23], s[38:39]
	ds_write_b32 v191, v86 offset:128
	s_or_b64 exec, exec, s[22:23]
	s_waitcnt lgkmcnt(0)
	v_lshl_add_u32 v89, v185, 2, s44
	ds_read_b128 v[90:93], v89 offset:224
	ds_read_b128 v[94:97], v89 offset:192
	ds_read_b128 v[98:101], v89 offset:160
	ds_read_b128 v[166:169], v89 offset:128
	s_waitcnt lgkmcnt(3)
	v_pk_mul_f32 v[34:35], v[34:35], v[92:93]
	s_waitcnt lgkmcnt(2)
	v_pk_mul_f32 v[30:31], v[30:31], v[96:97]
	s_waitcnt lgkmcnt(1)
	v_pk_mul_f32 v[26:27], v[26:27], v[100:101]
	s_waitcnt lgkmcnt(0)
	v_pk_mul_f32 v[22:23], v[22:23], v[168:169]
	v_pk_mul_f32 v[32:33], v[32:33], v[90:91]
	v_pk_mul_f32 v[28:29], v[28:29], v[94:95]
	v_pk_mul_f32 v[24:25], v[24:25], v[98:99]
	v_pk_mul_f32 v[20:21], v[20:21], v[166:167]
	v_pk_mul_f32 v[50:51], v[50:51], v[92:93]
	v_pk_mul_f32 v[46:47], v[46:47], v[96:97]
	v_pk_mul_f32 v[42:43], v[42:43], v[100:101]
	v_pk_mul_f32 v[38:39], v[38:39], v[168:169]
	v_pk_mul_f32 v[48:49], v[48:49], v[90:91]
	v_pk_mul_f32 v[44:45], v[44:45], v[94:95]
	v_pk_mul_f32 v[40:41], v[40:41], v[98:99]
	v_pk_mul_f32 v[36:37], v[36:37], v[166:167]
	v_pk_mul_f32 v[66:67], v[66:67], v[92:93]
	v_pk_mul_f32 v[62:63], v[62:63], v[96:97]
	v_pk_mul_f32 v[58:59], v[58:59], v[100:101]
	v_pk_mul_f32 v[54:55], v[54:55], v[168:169]
	v_pk_mul_f32 v[64:65], v[64:65], v[90:91]
	v_pk_mul_f32 v[60:61], v[60:61], v[94:95]
	v_pk_mul_f32 v[56:57], v[56:57], v[98:99]
	v_pk_mul_f32 v[52:53], v[52:53], v[166:167]
	v_pk_mul_f32 v[18:19], v[18:19], v[92:93]
	v_pk_mul_f32 v[14:15], v[14:15], v[96:97]
	v_pk_mul_f32 v[10:11], v[10:11], v[100:101]
	v_pk_mul_f32 v[6:7], v[6:7], v[168:169]
	v_pk_mul_f32 v[16:17], v[16:17], v[90:91]
	v_pk_mul_f32 v[12:13], v[12:13], v[94:95]
	v_pk_mul_f32 v[8:9], v[8:9], v[98:99]
	v_pk_mul_f32 v[4:5], v[4:5], v[166:167]

.Lam_done_3:
	v_max_f32_e32 v158, v86, v87
	v_max3_f32 v158, v158, v88, v89
	v_max3_f32 v158, v158, v90, v91
	v_max3_f32 v158, v158, v92, v93
	v_max3_f32 v158, v158, v94, v95
	v_max3_f32 v158, v158, v96, v97
	v_max3_f32 v158, v158, v98, v99
	v_max3_f32 v158, v158, v100, v101
	v_max3_f32 v158, v158, v70, v71
	v_max3_f32 v158, v158, v72, v73
	v_max3_f32 v158, v158, v74, v75
	v_max3_f32 v158, v158, v76, v77
	v_max3_f32 v158, v158, v78, v79
	v_max3_f32 v158, v158, v80, v81
	v_max3_f32 v158, v158, v82, v83
	v_max3_f32 v158, v158, v84, v85
	v_mov_b32_e32 v159, v158
	s_nop 1
	v_permlane32_swap_b32_e32 v158, v159
	v_max3_f32 v209, v212, v158, v159
	v_cmp_eq_u32_e32 vcc, 0xf149f2ca, v212
	s_nop 0
	s_cmp_eq_u64 vcc, exec
	s_cselect_b32 s100, 1, 0
	v_sub_f32_e32 v86, v86, v209
	v_exp_f32_e32 v159, v86
	v_sub_f32_e32 v86, v87, v209
	v_exp_f32_e32 v160, v86
	v_sub_f32_e32 v86, v88, v209
	v_exp_f32_e32 v161, v86
	v_sub_f32_e32 v86, v89, v209
	v_exp_f32_e32 v89, v86
	v_sub_f32_e32 v86, v90, v209
	v_exp_f32_e32 v90, v86
	v_sub_f32_e32 v86, v91, v209
	v_exp_f32_e32 v91, v86
	v_sub_f32_e32 v86, v92, v209
	v_exp_f32_e32 v92, v86
	v_sub_f32_e32 v86, v93, v209
	v_exp_f32_e32 v93, v86
	v_sub_f32_e32 v86, v94, v209
	v_exp_f32_e32 v94, v86
	v_sub_f32_e32 v86, v95, v209
	v_exp_f32_e32 v95, v86
	v_sub_f32_e32 v86, v96, v209
	v_exp_f32_e32 v96, v86
	v_sub_f32_e32 v86, v97, v209
	v_exp_f32_e32 v97, v86
	v_sub_f32_e32 v86, v98, v209
	v_exp_f32_e32 v98, v86
	v_sub_f32_e32 v86, v99, v209
	v_exp_f32_e32 v99, v86
	v_sub_f32_e32 v86, v100, v209
	v_sub_f32_e32 v158, v212, v209
	v_sub_f32_e32 v74, v74, v209
	v_exp_f32_e32 v100, v86
	v_sub_f32_e32 v86, v101, v209
	v_exp_f32_e32 v101, v86
	v_exp_f32_e32 v86, v158
	v_exp_f32_e32 v158, v74
	v_add_f32_e32 v74, 0, v159
	v_add_f32_e32 v74, v160, v74
	v_add_f32_e32 v74, v161, v74
	v_add_f32_e32 v74, v89, v74
	v_add_f32_e32 v74, v90, v74
	v_add_f32_e32 v74, v91, v74
	v_add_f32_e32 v74, v92, v74
	v_add_f32_e32 v74, v93, v74
	v_add_f32_e32 v74, v94, v74
	v_add_f32_e32 v74, v95, v74
	v_add_f32_e32 v74, v96, v74
	v_sub_f32_e32 v70, v70, v209
	v_add_f32_e32 v74, v97, v74
	v_sub_f32_e32 v71, v71, v209
	v_exp_f32_e32 v70, v70
	v_add_f32_e32 v74, v98, v74
	v_sub_f32_e32 v72, v72, v209
	v_exp_f32_e32 v71, v71
	v_add_f32_e32 v74, v99, v74
	v_sub_f32_e32 v73, v73, v209
	v_exp_f32_e32 v72, v72
	v_add_f32_e32 v74, v100, v74
	v_exp_f32_e32 v73, v73
	v_add_f32_e32 v74, v101, v74
	v_sub_f32_e32 v75, v75, v209
	v_add_f32_e32 v74, v70, v74
	v_sub_f32_e32 v76, v76, v209
	v_exp_f32_e32 v162, v75
	v_add_f32_e32 v74, v71, v74
	v_sub_f32_e32 v77, v77, v209
	v_exp_f32_e32 v163, v76
	v_add_f32_e32 v74, v72, v74
	v_sub_f32_e32 v78, v78, v209
	v_exp_f32_e32 v77, v77
	v_add_f32_e32 v74, v73, v74
	v_sub_f32_e32 v79, v79, v209
	v_exp_f32_e32 v164, v78
	v_add_f32_e32 v74, v158, v74
	v_sub_f32_e32 v80, v80, v209
	v_exp_f32_e32 v165, v79
	v_add_f32_e32 v74, v162, v74
	v_sub_f32_e32 v81, v81, v209
	v_exp_f32_e32 v174, v80
	v_add_f32_e32 v74, v163, v74
	v_sub_f32_e32 v82, v82, v209
	v_exp_f32_e32 v175, v81
	v_add_f32_e32 v74, v77, v74
	v_sub_f32_e32 v83, v83, v209
	v_exp_f32_e32 v176, v82
	v_add_f32_e32 v74, v164, v74
	v_sub_f32_e32 v84, v84, v209
	v_exp_f32_e32 v177, v83
	v_add_f32_e32 v74, v165, v74
	v_sub_f32_e32 v85, v85, v209
	v_exp_f32_e32 v178, v84
	v_add_f32_e32 v74, v174, v74
	v_exp_f32_e32 v179, v85
	v_add_f32_e32 v74, v175, v74
	v_add_f32_e32 v74, v176, v74
	v_add_f32_e32 v74, v177, v74
	v_add_f32_e32 v74, v178, v74
	v_add_f32_e32 v87, v179, v74
	v_mov_b32_e32 v88, v87
	s_nop 1
	v_permlane32_swap_b32_e32 v87, v88
	v_cmp_gt_f32_e32 vcc, 1.0, v86
	v_cvt_pk_bf16_f32 v82, v159, v160
	v_cvt_pk_bf16_f32 v83, v161, v89
	v_cvt_pk_bf16_f32 v84, v90, v91
	v_cvt_pk_bf16_f32 v85, v92, v93
	v_cvt_pk_bf16_f32 v78, v94, v95
	v_cvt_pk_bf16_f32 v79, v96, v97
	v_cvt_pk_bf16_f32 v80, v98, v99
	v_cvt_pk_bf16_f32 v81, v100, v101
	v_cvt_pk_bf16_f32 v74, v70, v71
	v_cvt_pk_bf16_f32 v75, v72, v73
	v_cvt_pk_bf16_f32 v76, v158, v162
	v_cvt_pk_bf16_f32 v77, v163, v77
	v_cvt_pk_bf16_f32 v70, v164, v165
	v_cvt_pk_bf16_f32 v71, v174, v175
	v_cvt_pk_bf16_f32 v72, v176, v177
	v_cvt_pk_bf16_f32 v73, v178, v179
	s_cmp_lg_u32 s100, 0
	s_cbranch_scc1 .LBB0_580
	s_cbranch_vccz .LBB0_580
	s_and_saveexec_b64 s[10:11], s[38:39]
	ds_write_b32 v191, v86 offset:128
	s_or_b64 exec, exec, s[10:11]
	s_waitcnt lgkmcnt(0)
	v_lshl_add_u32 v89, v185, 2, s44
	ds_read_b128 v[90:93], v89 offset:224
	ds_read_b128 v[94:97], v89 offset:192
	ds_read_b128 v[98:101], v89 offset:160
	ds_read_b128 v[158:161], v89 offset:128
	s_waitcnt lgkmcnt(3)
	v_pk_mul_f32 v[34:35], v[34:35], v[92:93]
	s_waitcnt lgkmcnt(2)
	v_pk_mul_f32 v[30:31], v[30:31], v[96:97]
	s_waitcnt lgkmcnt(1)
	v_pk_mul_f32 v[26:27], v[26:27], v[100:101]
	s_waitcnt lgkmcnt(0)
	v_pk_mul_f32 v[22:23], v[22:23], v[160:161]
	v_pk_mul_f32 v[32:33], v[32:33], v[90:91]
	v_pk_mul_f32 v[28:29], v[28:29], v[94:95]
	v_pk_mul_f32 v[24:25], v[24:25], v[98:99]
	v_pk_mul_f32 v[20:21], v[20:21], v[158:159]
	v_pk_mul_f32 v[50:51], v[50:51], v[92:93]
	v_pk_mul_f32 v[46:47], v[46:47], v[96:97]
	v_pk_mul_f32 v[42:43], v[42:43], v[100:101]
	v_pk_mul_f32 v[38:39], v[38:39], v[160:161]
	v_pk_mul_f32 v[48:49], v[48:49], v[90:91]
	v_pk_mul_f32 v[44:45], v[44:45], v[94:95]
	v_pk_mul_f32 v[40:41], v[40:41], v[98:99]
	v_pk_mul_f32 v[36:37], v[36:37], v[158:159]
	v_pk_mul_f32 v[66:67], v[66:67], v[92:93]
	v_pk_mul_f32 v[62:63], v[62:63], v[96:97]
	v_pk_mul_f32 v[58:59], v[58:59], v[100:101]
	v_pk_mul_f32 v[54:55], v[54:55], v[160:161]
	v_pk_mul_f32 v[64:65], v[64:65], v[90:91]
	v_pk_mul_f32 v[60:61], v[60:61], v[94:95]
	v_pk_mul_f32 v[56:57], v[56:57], v[98:99]
	v_pk_mul_f32 v[52:53], v[52:53], v[158:159]
	v_pk_mul_f32 v[18:19], v[18:19], v[92:93]
	v_pk_mul_f32 v[14:15], v[14:15], v[96:97]
	v_pk_mul_f32 v[10:11], v[10:11], v[100:101]
	v_pk_mul_f32 v[6:7], v[6:7], v[160:161]
	v_pk_mul_f32 v[16:17], v[16:17], v[90:91]
	v_pk_mul_f32 v[12:13], v[12:13], v[94:95]
	v_pk_mul_f32 v[8:9], v[8:9], v[98:99]
	v_pk_mul_f32 v[4:5], v[4:5], v[158:159]

.Lam_done_4:
	v_max_f32_e32 v134, v86, v87
	v_max3_f32 v134, v134, v88, v89
	v_max3_f32 v134, v134, v90, v91
	v_max3_f32 v134, v134, v92, v93
	v_max3_f32 v134, v134, v94, v95
	v_max3_f32 v134, v134, v96, v97
	v_max3_f32 v134, v134, v98, v99
	v_max3_f32 v134, v134, v100, v101
	v_max3_f32 v134, v134, v70, v71
	v_max3_f32 v134, v134, v72, v73
	v_max3_f32 v134, v134, v74, v75
	v_max3_f32 v134, v134, v76, v77
	v_max3_f32 v134, v134, v78, v79
	v_max3_f32 v134, v134, v80, v81
	v_max3_f32 v134, v134, v82, v83
	v_max3_f32 v134, v134, v84, v85
	v_mov_b32_e32 v135, v134
	s_nop 1
	v_permlane32_swap_b32_e32 v134, v135
	v_max3_f32 v210, v209, v134, v135
	v_cmp_eq_u32_e32 vcc, 0xf149f2ca, v209
	s_nop 0
	s_cmp_eq_u64 vcc, exec
	s_cselect_b32 s100, 1, 0
	v_sub_f32_e32 v86, v86, v210
	v_exp_f32_e32 v135, v86
	v_sub_f32_e32 v86, v87, v210
	v_exp_f32_e32 v136, v86
	v_sub_f32_e32 v86, v88, v210
	v_exp_f32_e32 v137, v86
	v_sub_f32_e32 v86, v89, v210
	v_exp_f32_e32 v89, v86
	v_sub_f32_e32 v86, v90, v210
	v_exp_f32_e32 v90, v86
	v_sub_f32_e32 v86, v91, v210
	v_exp_f32_e32 v91, v86
	v_sub_f32_e32 v86, v92, v210
	v_exp_f32_e32 v92, v86
	v_sub_f32_e32 v86, v93, v210
	v_exp_f32_e32 v93, v86
	v_sub_f32_e32 v86, v94, v210
	v_exp_f32_e32 v94, v86
	v_sub_f32_e32 v86, v95, v210
	v_exp_f32_e32 v95, v86
	v_sub_f32_e32 v86, v96, v210
	v_exp_f32_e32 v96, v86
	v_sub_f32_e32 v86, v97, v210
	v_exp_f32_e32 v97, v86
	v_sub_f32_e32 v86, v98, v210
	v_exp_f32_e32 v98, v86
	v_sub_f32_e32 v86, v99, v210
	v_exp_f32_e32 v99, v86
	v_sub_f32_e32 v86, v100, v210
	v_sub_f32_e32 v134, v209, v210
	v_sub_f32_e32 v74, v74, v210
	v_exp_f32_e32 v100, v86
	v_sub_f32_e32 v86, v101, v210
	v_exp_f32_e32 v101, v86
	v_exp_f32_e32 v86, v134
	v_exp_f32_e32 v134, v74
	v_add_f32_e32 v74, 0, v135
	v_add_f32_e32 v74, v136, v74
	v_add_f32_e32 v74, v137, v74
	v_add_f32_e32 v74, v89, v74
	v_add_f32_e32 v74, v90, v74
	v_add_f32_e32 v74, v91, v74
	v_add_f32_e32 v74, v92, v74
	v_add_f32_e32 v74, v93, v74
	v_add_f32_e32 v74, v94, v74
	v_add_f32_e32 v74, v95, v74
	v_add_f32_e32 v74, v96, v74
	v_sub_f32_e32 v70, v70, v210
	v_add_f32_e32 v74, v97, v74
	v_sub_f32_e32 v71, v71, v210
	v_exp_f32_e32 v70, v70
	v_add_f32_e32 v74, v98, v74
	v_sub_f32_e32 v72, v72, v210
	v_exp_f32_e32 v71, v71
	v_add_f32_e32 v74, v99, v74
	v_sub_f32_e32 v73, v73, v210
	v_exp_f32_e32 v72, v72
	v_add_f32_e32 v74, v100, v74
	v_exp_f32_e32 v73, v73
	v_add_f32_e32 v74, v101, v74
	v_sub_f32_e32 v75, v75, v210
	v_add_f32_e32 v74, v70, v74
	v_sub_f32_e32 v76, v76, v210
	v_exp_f32_e32 v138, v75
	v_add_f32_e32 v74, v71, v74
	v_sub_f32_e32 v77, v77, v210
	v_exp_f32_e32 v139, v76
	v_add_f32_e32 v74, v72, v74
	v_sub_f32_e32 v78, v78, v210
	v_exp_f32_e32 v77, v77
	v_add_f32_e32 v74, v73, v74
	v_sub_f32_e32 v79, v79, v210
	v_exp_f32_e32 v140, v78
	v_add_f32_e32 v74, v134, v74
	v_sub_f32_e32 v80, v80, v210
	v_exp_f32_e32 v141, v79
	v_add_f32_e32 v74, v138, v74
	v_sub_f32_e32 v81, v81, v210
	v_exp_f32_e32 v174, v80
	v_add_f32_e32 v74, v139, v74
	v_sub_f32_e32 v82, v82, v210
	v_exp_f32_e32 v175, v81
	v_add_f32_e32 v74, v77, v74
	v_sub_f32_e32 v83, v83, v210
	v_exp_f32_e32 v176, v82
	v_add_f32_e32 v74, v140, v74
	v_sub_f32_e32 v84, v84, v210
	v_exp_f32_e32 v177, v83
	v_add_f32_e32 v74, v141, v74
	v_sub_f32_e32 v85, v85, v210
	v_exp_f32_e32 v178, v84
	v_add_f32_e32 v74, v174, v74
	v_exp_f32_e32 v179, v85
	v_add_f32_e32 v74, v175, v74
	v_add_f32_e32 v74, v176, v74
	v_add_f32_e32 v74, v177, v74
	v_add_f32_e32 v74, v178, v74
	v_add_f32_e32 v87, v179, v74
	v_mov_b32_e32 v88, v87
	s_nop 1
	v_permlane32_swap_b32_e32 v87, v88
	v_cmp_gt_f32_e32 vcc, 1.0, v86
	v_cvt_pk_bf16_f32 v82, v135, v136
	v_cvt_pk_bf16_f32 v83, v137, v89
	v_cvt_pk_bf16_f32 v84, v90, v91
	v_cvt_pk_bf16_f32 v85, v92, v93
	v_cvt_pk_bf16_f32 v78, v94, v95
	v_cvt_pk_bf16_f32 v79, v96, v97
	v_cvt_pk_bf16_f32 v80, v98, v99
	v_cvt_pk_bf16_f32 v81, v100, v101
	v_cvt_pk_bf16_f32 v74, v70, v71
	v_cvt_pk_bf16_f32 v75, v72, v73
	v_cvt_pk_bf16_f32 v76, v134, v138
	v_cvt_pk_bf16_f32 v77, v139, v77
	v_cvt_pk_bf16_f32 v70, v140, v141
	v_cvt_pk_bf16_f32 v71, v174, v175
	v_cvt_pk_bf16_f32 v72, v176, v177
	v_cvt_pk_bf16_f32 v73, v178, v179
	s_cmp_lg_u32 s100, 0
	s_cbranch_scc1 .LBB0_587
	s_cbranch_vccz .LBB0_587
	s_and_saveexec_b64 s[26:27], s[38:39]
	ds_write_b32 v191, v86 offset:128
	s_or_b64 exec, exec, s[26:27]
	s_waitcnt lgkmcnt(0)
	v_lshl_add_u32 v89, v185, 2, s44
	ds_read_b128 v[90:93], v89 offset:224
	ds_read_b128 v[94:97], v89 offset:192
	ds_read_b128 v[98:101], v89 offset:160
	ds_read_b128 v[134:137], v89 offset:128
	s_waitcnt lgkmcnt(3)
	v_pk_mul_f32 v[34:35], v[34:35], v[92:93]
	s_waitcnt lgkmcnt(2)
	v_pk_mul_f32 v[30:31], v[30:31], v[96:97]
	s_waitcnt lgkmcnt(1)
	v_pk_mul_f32 v[26:27], v[26:27], v[100:101]
	s_waitcnt lgkmcnt(0)
	v_pk_mul_f32 v[22:23], v[22:23], v[136:137]
	v_pk_mul_f32 v[32:33], v[32:33], v[90:91]
	v_pk_mul_f32 v[28:29], v[28:29], v[94:95]
	v_pk_mul_f32 v[24:25], v[24:25], v[98:99]
	v_pk_mul_f32 v[20:21], v[20:21], v[134:135]
	v_pk_mul_f32 v[50:51], v[50:51], v[92:93]
	v_pk_mul_f32 v[46:47], v[46:47], v[96:97]
	v_pk_mul_f32 v[42:43], v[42:43], v[100:101]
	v_pk_mul_f32 v[38:39], v[38:39], v[136:137]
	v_pk_mul_f32 v[48:49], v[48:49], v[90:91]
	v_pk_mul_f32 v[44:45], v[44:45], v[94:95]
	v_pk_mul_f32 v[40:41], v[40:41], v[98:99]
	v_pk_mul_f32 v[36:37], v[36:37], v[134:135]
	v_pk_mul_f32 v[66:67], v[66:67], v[92:93]
	v_pk_mul_f32 v[62:63], v[62:63], v[96:97]
	v_pk_mul_f32 v[58:59], v[58:59], v[100:101]
	v_pk_mul_f32 v[54:55], v[54:55], v[136:137]
	v_pk_mul_f32 v[64:65], v[64:65], v[90:91]
	v_pk_mul_f32 v[60:61], v[60:61], v[94:95]
	v_pk_mul_f32 v[56:57], v[56:57], v[98:99]
	v_pk_mul_f32 v[52:53], v[52:53], v[134:135]
	v_pk_mul_f32 v[18:19], v[18:19], v[92:93]
	v_pk_mul_f32 v[14:15], v[14:15], v[96:97]
	v_pk_mul_f32 v[10:11], v[10:11], v[100:101]
	v_pk_mul_f32 v[6:7], v[6:7], v[136:137]
	v_pk_mul_f32 v[16:17], v[16:17], v[90:91]
	v_pk_mul_f32 v[12:13], v[12:13], v[94:95]
	v_pk_mul_f32 v[8:9], v[8:9], v[98:99]
	v_pk_mul_f32 v[4:5], v[4:5], v[134:135]

.Lam_done_5:
	v_max_f32_e32 v86, v102, v87
	v_max3_f32 v86, v86, v88, v89
	v_max3_f32 v86, v86, v90, v91
	v_max3_f32 v86, v86, v92, v93
	v_max3_f32 v86, v86, v94, v95
	v_max3_f32 v86, v86, v96, v97
	v_max3_f32 v86, v86, v98, v99
	v_max3_f32 v86, v86, v100, v101
	v_max3_f32 v86, v86, v70, v71
	v_max3_f32 v86, v86, v72, v73
	v_max3_f32 v86, v86, v74, v75
	v_max3_f32 v86, v86, v76, v77
	v_max3_f32 v86, v86, v78, v79
	v_max3_f32 v86, v86, v80, v81
	v_max3_f32 v86, v86, v82, v83
	v_max3_f32 v86, v86, v84, v85
	v_mov_b32_e32 v103, v86
	s_nop 1
	v_permlane32_swap_b32_e32 v86, v103
	v_max3_f32 v86, v210, v86, v103
	v_cmp_eq_u32_e32 vcc, 0xf149f2ca, v210
	s_nop 0
	s_cmp_eq_u64 vcc, exec
	s_cselect_b32 s100, 1, 0
	v_sub_f32_e32 v87, v87, v86
	v_exp_f32_e32 v104, v87
	v_sub_f32_e32 v87, v88, v86
	v_exp_f32_e32 v105, v87
	v_sub_f32_e32 v87, v89, v86
	v_exp_f32_e32 v106, v87
	v_sub_f32_e32 v87, v90, v86
	v_exp_f32_e32 v90, v87
	v_sub_f32_e32 v87, v91, v86
	v_exp_f32_e32 v91, v87
	v_sub_f32_e32 v87, v92, v86
	v_exp_f32_e32 v92, v87
	v_sub_f32_e32 v87, v93, v86
	v_exp_f32_e32 v93, v87
	v_sub_f32_e32 v87, v94, v86
	v_exp_f32_e32 v94, v87
	v_sub_f32_e32 v87, v95, v86
	v_exp_f32_e32 v95, v87
	v_sub_f32_e32 v87, v96, v86
	v_sub_f32_e32 v102, v102, v86
	v_exp_f32_e32 v96, v87
	v_sub_f32_e32 v87, v97, v86
	v_exp_f32_e32 v102, v102
	v_exp_f32_e32 v97, v87
	v_sub_f32_e32 v87, v98, v86
	v_exp_f32_e32 v98, v87
	v_sub_f32_e32 v87, v99, v86
	v_exp_f32_e32 v99, v87
	v_sub_f32_e32 v87, v100, v86
	v_sub_f32_e32 v103, v210, v86
	v_sub_f32_e32 v74, v74, v86
	v_exp_f32_e32 v100, v87
	v_sub_f32_e32 v87, v101, v86
	v_exp_f32_e32 v101, v87
	v_exp_f32_e32 v87, v103
	v_exp_f32_e32 v103, v74
	v_add_f32_e32 v74, 0, v102
	v_add_f32_e32 v74, v104, v74
	v_add_f32_e32 v74, v105, v74
	v_add_f32_e32 v74, v106, v74
	v_add_f32_e32 v74, v90, v74
	v_add_f32_e32 v74, v91, v74
	v_add_f32_e32 v74, v92, v74
	v_add_f32_e32 v74, v93, v74
	v_add_f32_e32 v74, v94, v74
	v_add_f32_e32 v74, v95, v74
	v_add_f32_e32 v74, v96, v74
	v_sub_f32_e32 v70, v70, v86
	v_add_f32_e32 v74, v97, v74
	v_sub_f32_e32 v71, v71, v86
	v_exp_f32_e32 v70, v70
	v_add_f32_e32 v74, v98, v74
	v_sub_f32_e32 v72, v72, v86
	v_exp_f32_e32 v71, v71
	v_add_f32_e32 v74, v99, v74
	v_sub_f32_e32 v73, v73, v86
	v_exp_f32_e32 v72, v72
	v_add_f32_e32 v74, v100, v74
	v_exp_f32_e32 v73, v73
	v_add_f32_e32 v74, v101, v74
	v_sub_f32_e32 v75, v75, v86
	v_add_f32_e32 v74, v70, v74
	v_sub_f32_e32 v76, v76, v86
	v_exp_f32_e32 v107, v75
	v_add_f32_e32 v74, v71, v74
	v_sub_f32_e32 v77, v77, v86
	v_exp_f32_e32 v108, v76
	v_add_f32_e32 v74, v72, v74
	v_sub_f32_e32 v78, v78, v86
	v_exp_f32_e32 v77, v77
	v_add_f32_e32 v74, v73, v74
	v_sub_f32_e32 v79, v79, v86
	v_exp_f32_e32 v109, v78
	v_add_f32_e32 v74, v103, v74
	v_sub_f32_e32 v80, v80, v86
	v_exp_f32_e32 v110, v79
	v_add_f32_e32 v74, v107, v74
	v_sub_f32_e32 v81, v81, v86
	v_exp_f32_e32 v111, v80
	v_add_f32_e32 v74, v108, v74
	v_sub_f32_e32 v82, v82, v86
	v_exp_f32_e32 v112, v81
	v_add_f32_e32 v74, v77, v74
	v_sub_f32_e32 v83, v83, v86
	v_exp_f32_e32 v113, v82
	v_add_f32_e32 v74, v109, v74
	v_sub_f32_e32 v84, v84, v86
	v_exp_f32_e32 v114, v83
	v_add_f32_e32 v74, v110, v74
	v_sub_f32_e32 v85, v85, v86
	v_exp_f32_e32 v115, v84
	v_add_f32_e32 v74, v111, v74
	v_exp_f32_e32 v116, v85
	v_add_f32_e32 v74, v112, v74
	v_add_f32_e32 v74, v113, v74
	v_add_f32_e32 v74, v114, v74
	v_add_f32_e32 v74, v115, v74
	v_add_f32_e32 v88, v116, v74
	v_mov_b32_e32 v89, v88
	s_nop 1
	v_permlane32_swap_b32_e32 v88, v89
	v_cmp_gt_f32_e32 vcc, 1.0, v87
	v_cvt_pk_bf16_f32 v82, v102, v104
	v_cvt_pk_bf16_f32 v83, v105, v106
	v_cvt_pk_bf16_f32 v84, v90, v91
	v_cvt_pk_bf16_f32 v85, v92, v93
	v_cvt_pk_bf16_f32 v78, v94, v95
	v_cvt_pk_bf16_f32 v79, v96, v97
	v_cvt_pk_bf16_f32 v80, v98, v99
	v_cvt_pk_bf16_f32 v81, v100, v101
	v_cvt_pk_bf16_f32 v74, v70, v71
	v_cvt_pk_bf16_f32 v75, v72, v73
	v_cvt_pk_bf16_f32 v76, v103, v107
	v_cvt_pk_bf16_f32 v77, v108, v77
	v_cvt_pk_bf16_f32 v70, v109, v110
	v_cvt_pk_bf16_f32 v71, v111, v112
	v_cvt_pk_bf16_f32 v72, v113, v114
	v_cvt_pk_bf16_f32 v73, v115, v116
	s_cmp_lg_u32 s100, 0
	s_cbranch_scc1 .LBB0_594
	s_cbranch_vccz .LBB0_594
	s_and_saveexec_b64 s[12:13], s[38:39]
	ds_write_b32 v191, v87 offset:128
	s_or_b64 exec, exec, s[12:13]
	s_waitcnt lgkmcnt(0)
	v_lshl_add_u32 v102, v185, 2, s44
	ds_read_b128 v[90:93], v102 offset:224
	ds_read_b128 v[94:97], v102 offset:192
	ds_read_b128 v[98:101], v102 offset:160
	ds_read_b128 v[102:105], v102 offset:128
	s_waitcnt lgkmcnt(3)
	v_pk_mul_f32 v[34:35], v[34:35], v[92:93]
	s_waitcnt lgkmcnt(2)
	v_pk_mul_f32 v[30:31], v[30:31], v[96:97]
	s_waitcnt lgkmcnt(1)
	v_pk_mul_f32 v[26:27], v[26:27], v[100:101]
	s_waitcnt lgkmcnt(0)
	v_pk_mul_f32 v[22:23], v[22:23], v[104:105]
	v_pk_mul_f32 v[32:33], v[32:33], v[90:91]
	v_pk_mul_f32 v[28:29], v[28:29], v[94:95]
	v_pk_mul_f32 v[24:25], v[24:25], v[98:99]
	v_pk_mul_f32 v[20:21], v[20:21], v[102:103]
	v_pk_mul_f32 v[50:51], v[50:51], v[92:93]
	v_pk_mul_f32 v[46:47], v[46:47], v[96:97]
	v_pk_mul_f32 v[42:43], v[42:43], v[100:101]
	v_pk_mul_f32 v[38:39], v[38:39], v[104:105]
	v_pk_mul_f32 v[48:49], v[48:49], v[90:91]
	v_pk_mul_f32 v[44:45], v[44:45], v[94:95]
	v_pk_mul_f32 v[40:41], v[40:41], v[98:99]
	v_pk_mul_f32 v[36:37], v[36:37], v[102:103]
	v_pk_mul_f32 v[66:67], v[66:67], v[92:93]
	v_pk_mul_f32 v[62:63], v[62:63], v[96:97]
	v_pk_mul_f32 v[58:59], v[58:59], v[100:101]
	v_pk_mul_f32 v[54:55], v[54:55], v[104:105]
	v_pk_mul_f32 v[64:65], v[64:65], v[90:91]
	v_pk_mul_f32 v[60:61], v[60:61], v[94:95]
	v_pk_mul_f32 v[56:57], v[56:57], v[98:99]
	v_pk_mul_f32 v[52:53], v[52:53], v[102:103]
	v_pk_mul_f32 v[18:19], v[18:19], v[92:93]
	v_pk_mul_f32 v[14:15], v[14:15], v[96:97]
	v_pk_mul_f32 v[10:11], v[10:11], v[100:101]
	v_pk_mul_f32 v[6:7], v[6:7], v[104:105]
	v_pk_mul_f32 v[16:17], v[16:17], v[90:91]
	v_pk_mul_f32 v[12:13], v[12:13], v[94:95]
	v_pk_mul_f32 v[8:9], v[8:9], v[98:99]
	v_pk_mul_f32 v[4:5], v[4:5], v[102:103]

.LBB0_700:
	s_nop 0
	v_max_f32_e32 v123, v70, v71
	v_max3_f32 v123, v123, v72, v73
	v_max3_f32 v122, v86, v87, v88
	v_max3_f32 v123, v123, v74, v75
	v_max3_f32 v122, v122, v89, v90
	v_max3_f32 v123, v123, v76, v77
	v_max3_f32 v122, v122, v91, v92
	v_max3_f32 v123, v123, v78, v79
	v_max3_f32 v122, v122, v93, v94
	v_max3_f32 v123, v123, v80, v81
	v_max3_f32 v122, v122, v95, v96
	v_max3_f32 v123, v123, v82, v83
	v_cndmask_b32_e32 v5, v167, v166, vcc
	v_max3_f32 v122, v122, v97, v98
	v_max3_f32 v123, v123, v84, v85
	v_max3_f32 v122, v122, v99, v100
	v_add_f32_e32 v123, v5, v123
	v_max3_f32 v122, v122, v101, v123
	v_mov_b32_e32 v123, v122
	s_nop 1
	v_permlane32_swap_b32_e32 v122, v123
	v_mul_f32_e64 v2, v162, |v4|
	v_max_f32_e32 v122, v122, v123
	v_fmac_f32_e32 v2, 0x3e38aa3b, v122
	v_sub_f32_e32 v122, v2, v168
	v_cmp_ge_f32_e32 vcc, s79, v122
	v_max_f32_e32 v2, v168, v2
	s_cmp_eq_u64 vcc, exec
	s_cselect_b64 vcc, -1, 0
	v_sub_f32_e32 v122, v168, v2
	v_cndmask_b32_e32 v168, v2, v168, vcc
	v_fma_f32 v4, v162, |v4|, -v168
	v_fmamk_f32 v86, v86, 0x3e38aa3b, v4
	v_exp_f32_e32 v86, v86
	v_fmamk_f32 v87, v87, 0x3e38aa3b, v4
	v_exp_f32_e32 v87, v87
	v_fmamk_f32 v88, v88, 0x3e38aa3b, v4
	v_exp_f32_e32 v88, v88
	v_fmamk_f32 v89, v89, 0x3e38aa3b, v4
	v_fmamk_f32 v90, v90, 0x3e38aa3b, v4
	v_fmamk_f32 v91, v91, 0x3e38aa3b, v4
	v_fmamk_f32 v92, v92, 0x3e38aa3b, v4
	v_fmamk_f32 v93, v93, 0x3e38aa3b, v4
	v_fmamk_f32 v94, v94, 0x3e38aa3b, v4
	v_fmamk_f32 v95, v95, 0x3e38aa3b, v4
	v_fmamk_f32 v96, v96, 0x3e38aa3b, v4
	v_fmamk_f32 v97, v97, 0x3e38aa3b, v4
	v_fmamk_f32 v98, v98, 0x3e38aa3b, v4
	v_fmamk_f32 v99, v99, 0x3e38aa3b, v4
	v_fmamk_f32 v100, v100, 0x3e38aa3b, v4
	v_fmamk_f32 v101, v101, 0x3e38aa3b, v4
	v_fmac_f32_e32 v4, 0x3e38aa3b, v5
	v_exp_f32_e32 v89, v89
	v_fmamk_f32 v5, v70, 0x3e38aa3b, v4
	v_fmamk_f32 v70, v71, 0x3e38aa3b, v4
	v_fmamk_f32 v71, v72, 0x3e38aa3b, v4
	v_fmamk_f32 v72, v73, 0x3e38aa3b, v4
	v_fmamk_f32 v73, v74, 0x3e38aa3b, v4
	v_fmamk_f32 v74, v75, 0x3e38aa3b, v4
	v_fmamk_f32 v75, v76, 0x3e38aa3b, v4
	v_fmamk_f32 v76, v77, 0x3e38aa3b, v4
	v_fmamk_f32 v77, v78, 0x3e38aa3b, v4
	v_fmamk_f32 v78, v79, 0x3e38aa3b, v4
	v_fmamk_f32 v79, v80, 0x3e38aa3b, v4
	v_fmamk_f32 v80, v81, 0x3e38aa3b, v4
	v_fmamk_f32 v81, v82, 0x3e38aa3b, v4
	v_fmamk_f32 v82, v83, 0x3e38aa3b, v4
	v_fmamk_f32 v83, v84, 0x3e38aa3b, v4
	v_fmac_f32_e32 v4, 0x3e38aa3b, v85
	v_exp_f32_e32 v90, v90
	v_exp_f32_e32 v85, v4
	v_exp_f32_e32 v91, v91
	v_add_f32_e32 v4, v87, v86
	v_exp_f32_e32 v92, v92
	v_add_f32_e32 v4, v88, v4
	v_exp_f32_e32 v93, v93
	v_add_f32_e32 v4, v89, v4
	v_exp_f32_e32 v94, v94
	v_add_f32_e32 v4, v90, v4
	v_exp_f32_e32 v95, v95
	v_add_f32_e32 v4, v91, v4
	v_exp_f32_e32 v96, v96
	v_add_f32_e32 v4, v92, v4
	v_exp_f32_e32 v97, v97
	v_add_f32_e32 v4, v93, v4
	v_exp_f32_e32 v98, v98
	v_add_f32_e32 v4, v94, v4
	v_exp_f32_e32 v99, v99
	v_add_f32_e32 v4, v95, v4
	v_exp_f32_e32 v100, v100
	v_add_f32_e32 v4, v96, v4
	v_exp_f32_e32 v101, v101
	v_add_f32_e32 v4, v97, v4
	v_exp_f32_e32 v84, v5
	v_add_f32_e32 v4, v98, v4
	v_exp_f32_e32 v70, v70
	v_add_f32_e32 v4, v99, v4
	v_exp_f32_e32 v71, v71
	v_add_f32_e32 v4, v100, v4
	v_exp_f32_e32 v72, v72
	v_add_f32_e32 v4, v101, v4
	v_exp_f32_e32 v73, v73
	v_add_f32_e32 v4, v84, v4
	v_exp_f32_e32 v74, v74
	v_add_f32_e32 v4, v70, v4
	v_exp_f32_e32 v75, v75
	v_add_f32_e32 v4, v71, v4
	v_exp_f32_e32 v76, v76
	v_add_f32_e32 v4, v72, v4
	v_exp_f32_e32 v77, v77
	v_add_f32_e32 v4, v73, v4
	v_exp_f32_e32 v78, v78
	v_add_f32_e32 v4, v74, v4
	v_exp_f32_e32 v79, v79
	v_add_f32_e32 v4, v75, v4
	v_exp_f32_e32 v80, v80
	v_add_f32_e32 v4, v76, v4
	v_exp_f32_e32 v81, v81
	v_add_f32_e32 v4, v77, v4
	v_exp_f32_e32 v82, v82
	v_add_f32_e32 v4, v78, v4
	v_exp_f32_e32 v83, v83
	v_add_f32_e32 v4, v79, v4
	v_add_f32_e32 v4, v80, v4
	v_exp_f32_e32 v122, v122
	v_add_f32_e32 v4, v81, v4
	v_add_f32_e32 v4, v82, v4
	v_add_f32_e32 v4, v83, v4
	v_add_f32_e32 v4, v85, v4
	v_cndmask_b32_e64 v2, v122, 1.0, vcc
	v_mov_b32_e32 v5, v4
	s_nop 1
	v_permlane32_swap_b32_e32 v4, v5
	v_cmp_gt_f32_e32 vcc, 1.0, v2
	v_cvt_pk_bf16_f32 v134, v86, v87
	v_cvt_pk_bf16_f32 v135, v88, v89
	v_cvt_pk_bf16_f32 v136, v90, v91
	v_cvt_pk_bf16_f32 v137, v92, v93
	v_cvt_pk_bf16_f32 v130, v94, v95
	v_cvt_pk_bf16_f32 v131, v96, v97
	v_cvt_pk_bf16_f32 v132, v98, v99
	v_cvt_pk_bf16_f32 v133, v100, v101
	v_cvt_pk_bf16_f32 v126, v84, v70
	v_cvt_pk_bf16_f32 v127, v71, v72
	v_cvt_pk_bf16_f32 v128, v73, v74
	v_cvt_pk_bf16_f32 v129, v75, v76
	v_cvt_pk_bf16_f32 v122, v77, v78
	v_cvt_pk_bf16_f32 v123, v79, v80
	v_cvt_pk_bf16_f32 v124, v81, v82
	v_cvt_pk_bf16_f32 v125, v83, v85
	s_cbranch_vccz .LBB0_704
	s_and_saveexec_b64 s[12:13], s[40:41]
	ds_write_b32 v169, v2 offset:128
	s_or_b64 exec, exec, s[12:13]
	s_waitcnt lgkmcnt(0)
	v_add_u32_e32 v82, s26, v138
	ds_read_b128 v[70:73], v82 offset:224
	ds_read_b128 v[74:77], v82 offset:192
	ds_read_b128 v[78:81], v82 offset:160
	ds_read_b128 v[82:85], v82 offset:128
	s_waitcnt lgkmcnt(0)
	v_pk_mul_f32 v[66:67], v[66:67], v[70:71]
	v_pk_mul_f32 v[62:63], v[62:63], v[74:75]
	v_pk_mul_f32 v[58:59], v[58:59], v[78:79]
	v_pk_mul_f32 v[68:69], v[68:69], v[72:73]
	v_pk_mul_f32 v[64:65], v[64:65], v[76:77]
	v_pk_mul_f32 v[60:61], v[60:61], v[80:81]
	v_pk_mul_f32 v[56:57], v[56:57], v[84:85]
	v_pk_mul_f32 v[54:55], v[54:55], v[82:83]
	v_pk_mul_f32 v[50:51], v[50:51], v[70:71]
	v_pk_mul_f32 v[46:47], v[46:47], v[74:75]
	v_pk_mul_f32 v[42:43], v[42:43], v[78:79]
	v_pk_mul_f32 v[52:53], v[52:53], v[72:73]
	v_pk_mul_f32 v[48:49], v[48:49], v[76:77]
	v_pk_mul_f32 v[44:45], v[44:45], v[80:81]
	v_pk_mul_f32 v[40:41], v[40:41], v[84:85]
	v_pk_mul_f32 v[38:39], v[38:39], v[82:83]
	v_pk_mul_f32 v[34:35], v[34:35], v[70:71]
	v_pk_mul_f32 v[30:31], v[30:31], v[74:75]
	v_pk_mul_f32 v[26:27], v[26:27], v[78:79]
	v_pk_mul_f32 v[36:37], v[36:37], v[72:73]
	v_pk_mul_f32 v[32:33], v[32:33], v[76:77]
	v_pk_mul_f32 v[28:29], v[28:29], v[80:81]
	v_pk_mul_f32 v[24:25], v[24:25], v[84:85]
	v_pk_mul_f32 v[22:23], v[22:23], v[82:83]
	v_pk_mul_f32 v[18:19], v[18:19], v[70:71]
	v_pk_mul_f32 v[14:15], v[14:15], v[74:75]
	v_pk_mul_f32 v[10:11], v[10:11], v[78:79]
	v_pk_mul_f32 v[20:21], v[20:21], v[72:73]
	v_pk_mul_f32 v[16:17], v[16:17], v[76:77]
	v_pk_mul_f32 v[12:13], v[12:13], v[80:81]
	v_pk_mul_f32 v[8:9], v[8:9], v[84:85]
	v_pk_mul_f32 v[6:7], v[6:7], v[82:83]
